# post-attention grid barrier: every arriving workgroup leader issues buffer_wbl2 sc1 before its arrival so the dirty L2 lines drain while the stragglers finish; on top of eb6
# baseline (speedup 1.0000x reference)
.LBB0_1175:
	v_readlane_b32 s0, v255, 27
	v_readlane_b32 s2, v255, 7
	s_add_i32 s0, s0, 2
	v_readlane_b32 s3, v255, 8
	s_cmp_ge_i32 s0, s3
	s_mov_b32 s72, 0x3fb8aa3b
	s_mov_b32 s73, 0xc2ce8ed0
	s_mov_b32 s74, 0x42b17218
	s_cbranch_scc1 .LBB0_1229
	v_readlane_b32 s4, v255, 5
	v_readlane_b32 s5, v255, 6
	v_readlane_b32 s0, v255, 9
	v_readlane_b32 s1, v255, 2
	s_mov_b32 s2, s97
	v_mbcnt_lo_u32_b32 v0, -1, 0
	v_mbcnt_hi_u32_b32 v0, -1, v0
	s_waitcnt vmcnt(0)
	s_waitcnt vmcnt(0) lgkmcnt(0)
	v_readlane_b32 s1, v255, 12
	s_barrier
	s_nop 0
	v_cmp_eq_u32_e32 vcc, s1, v0
	s_and_saveexec_b64 s[6:7], vcc
	s_cbranch_execz .LBB0_1228
	buffer_wbl2 sc1
	v_readlane_b32 s1, v255, 10
	s_waitcnt vmcnt(0) expcnt(0) lgkmcnt(0)
	s_nop 0
	v_mov_b32_e32 v0, s1
	ds_read_b32 v3, v0
	ds_read_b32 v0, v0 offset:4
	s_waitcnt lgkmcnt(1)
	v_cmp_ne_u32_e32 vcc, 0, v3
	s_cbranch_vccnz .LBB0_1192
	v_readlane_b32 s8, v255, 3
	v_readlane_b32 s9, v255, 4
	s_load_dwordx2 s[2:3], s[8:9], 0x4
	s_add_u32 s8, s4, 0x1000
	s_addc_u32 s9, s5, 0
	s_add_u32 s46, s4, 0x1100
	s_addc_u32 s47, s5, 0
	s_add_u32 s48, s4, 0x1200
	v_readlane_b32 s1, v255, 2
	s_addc_u32 s49, s5, 0
	s_waitcnt lgkmcnt(0)
	s_mul_i32 s1, s2, s1
	s_add_u32 s50, s4, 0x1300
	s_mul_i32 s1, s1, s3
	s_addc_u32 s51, s5, 0
	s_mov_b32 s2, 1
	s_branch .LBB0_1180
